# fc2 K loop: next-next slab issued right after the compute (extra workgroup barrier), counted vmcnt(7) wait: two slabs in flight with the same two LDS buffers
# baseline (speedup 1.0000x reference)
.LBB0_540:
	v_readlane_b32 s24, v247, 39
	s_cmp_lt_i32 s16, 1
	v_readlane_b32 s25, v247, 40
	s_cbranch_scc1 .LBB0_563
	s_mov_b32 s8, s28
	s_ashr_i32 s9, s28, 31
	v_lshrrev_b32_e32 v10, 4, v0
	s_lshl_b64 s[0:1], s[8:9], 23
	v_readlane_b32 s2, v248, 39
	v_xor_b32_e32 v3, v10, v0
	s_add_u32 s6, s2, s0
	v_readlane_b32 s2, v248, 40
	v_ashrrev_i32_e32 v2, 3, v0
	v_lshlrev_b32_e32 v3, 3, v3
	s_addc_u32 s7, s2, s1
	v_and_b32_e32 v4, 56, v3
	v_ashrrev_i32_e32 v3, 31, v2
	v_readlane_b32 s2, v249, 10
	v_lshlrev_b64 v[6:7], 12, v[2:3]
	v_lshlrev_b64 v[2:3], 13, v[2:3]
	v_readlane_b32 s3, v249, 11
	v_lshlrev_b32_e32 v152, 1, v4
	v_ashrrev_i32_e32 v1, 7, v0
	v_lshl_add_u64 v[8:9], s[2:3], 0, v[2:3]
	v_lshl_add_u64 v[48:49], v[8:9], 0, v[152:153]
	v_lshl_add_u64 v[8:9], s[6:7], 0, v[2:3]
	v_and_b32_e32 v62, 15, v0
	v_lshl_add_u64 v[50:51], v[8:9], 0, v[152:153]
	v_bfe_u32 v8, v0, 4, 2
	v_mul_lo_u32 v64, v1, 48
	v_bfe_u32 v9, v0, 1, 3
	v_or_b32_e32 v1, v64, v62
	v_bitop3_b32 v11, v10, v9, 3 bitop3:0x6c
	v_bitop3_b32 v8, v8, v9, 4 bitop3:0x36
	v_lshlrev_b32_e32 v11, 3, v11
	v_lshlrev_b32_e32 v1, 6, v1
	v_lshlrev_b32_e32 v12, 6, v0
	v_lshlrev_b32_e32 v8, 3, v8
	v_and_b32_e32 v5, 64, v0
	v_lshlrev_b32_e32 v63, 4, v0
	v_or_b32_e32 v65, v1, v11
	v_and_b32_e32 v12, 0x13c0, v12
	v_or_b32_e32 v67, v8, v1
	v_lshrrev_b32_e32 v1, 2, v0
	v_bitop3_b32 v0, v10, 7, v0 bitop3:0x48
	s_add_u32 s0, s24, s0
	v_or_b32_e32 v66, v11, v12
	v_or_b32_e32 v68, v8, v12
	v_lshl_or_b32 v2, v0, 4, v2
	v_mov_b32_e32 v150, v2
	s_addc_u32 s1, s25, s1
	s_mul_i32 s17, s28, 3
	v_and_or_b32 v69, v1, 12, v5
	v_or_b32_e32 v70, 16, v62
	v_or_b32_e32 v71, 32, v62
	v_lshlrev_b32_e32 v72, 1, v65
	v_lshlrev_b32_e32 v73, 1, v66
	v_lshlrev_b32_e32 v74, 1, v67
	v_lshlrev_b32_e32 v75, 1, v68
	v_lshl_add_u64 v[52:53], s[24:25], 0, v[2:3]
	v_lshl_add_u64 v[54:55], s[0:1], 0, v[2:3]
	s_mov_b32 s18, 0
	s_mov_b64 s[8:9], 0
	v_lshlrev_b64 v[56:57], 1, v[6:7]
	v_lshlrev_b32_e32 v152, 1, v4
	s_branch .LBB0_543

.LBB0_559:
	v_readlane_b32 s30, v249, 10
	v_readlane_b32 s31, v249, 11
	v_readfirstlane_b32 s29, v63
	s_add_u32 s30, s30, s0
	s_addc_u32 s31, s31, s1
	s_add_u32 s30, s30, 0x80
	s_addc_u32 s31, s31, 0
	s_add_u32 s34, s6, s14
	s_addc_u32 s35, s7, s15
	s_add_u32 s34, s34, 0x80
	s_addc_u32 s35, s35, 0
	s_mov_b32 s21, 0
	s_add_u32 s9, s29, 0x8000
	s_add_u32 m0, s9, 0x0
	s_nop 0
	global_load_lds_dwordx4 v150, s[30:31]
	s_add_u32 m0, s9, 0x1000
	s_add_u32 s22, s30, 0x40000
	s_addc_u32 s23, s31, 0
	global_load_lds_dwordx4 v150, s[22:23]
	s_add_u32 m0, s9, 0x2000
	s_add_u32 s22, s30, 0x80000
	s_addc_u32 s23, s31, 0
	global_load_lds_dwordx4 v150, s[22:23]
	s_add_u32 m0, s9, 0x4000
	s_nop 0
	global_load_lds_dwordx4 v150, s[34:35]
	s_add_u32 m0, s9, 0x5000
	s_add_u32 s22, s34, 0x40000
	s_addc_u32 s23, s35, 0
	global_load_lds_dwordx4 v150, s[22:23]
	s_add_u32 m0, s9, 0x6000
	s_add_u32 s22, s34, 0x80000
	s_addc_u32 s23, s35, 0
	global_load_lds_dwordx4 v150, s[22:23]
	s_add_u32 m0, s9, 0x7000
	s_add_u32 s22, s34, 0xc0000
	s_addc_u32 s23, s35, 0
	global_load_lds_dwordx4 v150, s[22:23]
	s_add_u32 s30, s30, 0x80
	s_addc_u32 s31, s31, 0
	s_add_u32 s34, s34, 0x80
	s_addc_u32 s35, s35, 0
	v_mov_b32_e32 v0, 0
	v_lshl_add_u64 v[58:59], v[52:53], 0, s[0:1]
	v_lshl_add_u64 v[60:61], v[54:55], 0, s[14:15]
	s_mov_b64 s[14:15], 0
	s_mov_b32 s0, 0
	s_movk_i32 s1, 0x2000
	v_mov_b32_e32 v1, v0
	v_mov_b32_e32 v2, v0
	v_mov_b32_e32 v3, v0
	v_mov_b32_e32 v4, v0
	v_mov_b32_e32 v5, v0
	v_mov_b32_e32 v6, v0
	v_mov_b32_e32 v7, v0
	v_mov_b32_e32 v8, v0
	v_mov_b32_e32 v9, v0
	v_mov_b32_e32 v10, v0
	v_mov_b32_e32 v11, v0
	v_mov_b32_e32 v12, v0
	v_mov_b32_e32 v13, v0
	v_mov_b32_e32 v14, v0
	v_mov_b32_e32 v15, v0
	v_mov_b32_e32 v16, v0
	v_mov_b32_e32 v17, v0
	v_mov_b32_e32 v18, v0
	v_mov_b32_e32 v19, v0
	v_mov_b32_e32 v20, v0
	v_mov_b32_e32 v21, v0
	v_mov_b32_e32 v22, v0
	v_mov_b32_e32 v23, v0
	v_mov_b32_e32 v24, v0
	v_mov_b32_e32 v25, v0
	v_mov_b32_e32 v26, v0
	v_mov_b32_e32 v27, v0
	v_mov_b32_e32 v28, v0
	v_mov_b32_e32 v29, v0
	v_mov_b32_e32 v30, v0
	v_mov_b32_e32 v31, v0
	v_mov_b32_e32 v32, v0
	v_mov_b32_e32 v33, v0
	v_mov_b32_e32 v34, v0
	v_mov_b32_e32 v35, v0
	v_mov_b32_e32 v36, v0
	v_mov_b32_e32 v37, v0
	v_mov_b32_e32 v38, v0
	v_mov_b32_e32 v39, v0
	v_mov_b32_e32 v40, v0
	v_mov_b32_e32 v41, v0
	v_mov_b32_e32 v42, v0
	v_mov_b32_e32 v43, v0
	v_mov_b32_e32 v44, v0
	v_mov_b32_e32 v45, v0
	v_mov_b32_e32 v46, v0
	v_mov_b32_e32 v47, v0
.LBB0_560:
	s_waitcnt vmcnt(7)
	s_barrier
	s_mov_b32 s9, s21
	v_lshl_add_u32 v90, v65, 1, s9
	v_lshl_or_b32 v106, v66, 1, s9
	ds_read_b128 v[82:85], v90
	ds_read_b128 v[86:89], v90 offset:2048
	ds_read_b128 v[90:93], v90 offset:4096
	ds_read_b128 v[94:97], v106 offset:16384
	ds_read_b128 v[98:101], v106 offset:18432
	ds_read_b128 v[102:105], v106 offset:20480
	ds_read_b128 v[106:109], v106 offset:22528
	s_waitcnt lgkmcnt(0)
	v_mfma_f32_16x16x32_bf16 v[32:35], v[106:109], v[82:85], v[32:35]
	s_add_u32 s14, s14, 0x80
	s_addc_u32 s15, s15, 0
	s_addk_i32 s0, 0x4000
	v_mfma_f32_16x16x32_bf16 v[16:19], v[106:109], v[86:89], v[16:19]
	s_addk_i32 s1, 0x2000
	s_cmpk_eq_i32 s14, 0x1f80
	v_mfma_f32_16x16x32_bf16 v[12:15], v[94:97], v[90:93], v[12:15]
	v_mfma_f32_16x16x32_bf16 v[8:11], v[98:101], v[90:93], v[8:11]
	v_mfma_f32_16x16x32_bf16 v[4:7], v[102:105], v[90:93], v[4:7]
	v_mfma_f32_16x16x32_bf16 v[0:3], v[106:109], v[90:93], v[0:3]
	v_lshl_add_u32 v90, v67, 1, s9
	v_lshl_or_b32 v106, v68, 1, s9
	v_mfma_f32_16x16x32_bf16 v[44:47], v[94:97], v[82:85], v[44:47]
	v_mfma_f32_16x16x32_bf16 v[40:43], v[98:101], v[82:85], v[40:43]
	v_mfma_f32_16x16x32_bf16 v[36:39], v[102:105], v[82:85], v[36:39]
	v_mfma_f32_16x16x32_bf16 v[28:31], v[94:97], v[86:89], v[28:31]
	v_mfma_f32_16x16x32_bf16 v[24:27], v[98:101], v[86:89], v[24:27]
	v_mfma_f32_16x16x32_bf16 v[20:23], v[102:105], v[86:89], v[20:23]
	ds_read_b128 v[82:85], v90
	ds_read_b128 v[86:89], v90 offset:2048
	ds_read_b128 v[90:93], v90 offset:4096
	ds_read_b128 v[94:97], v106 offset:16384
	ds_read_b128 v[98:101], v106 offset:18432
	ds_read_b128 v[102:105], v106 offset:20480
	ds_read_b128 v[106:109], v106 offset:22528
	s_waitcnt lgkmcnt(0)
	v_mfma_f32_16x16x32_bf16 v[44:47], v[94:97], v[82:85], v[44:47]
	v_mfma_f32_16x16x32_bf16 v[40:43], v[98:101], v[82:85], v[40:43]
	v_mfma_f32_16x16x32_bf16 v[36:39], v[102:105], v[82:85], v[36:39]
	v_mfma_f32_16x16x32_bf16 v[32:35], v[106:109], v[82:85], v[32:35]
	v_mfma_f32_16x16x32_bf16 v[28:31], v[94:97], v[86:89], v[28:31]
	v_mfma_f32_16x16x32_bf16 v[24:27], v[98:101], v[86:89], v[24:27]
	v_mfma_f32_16x16x32_bf16 v[20:23], v[102:105], v[86:89], v[20:23]
	v_mfma_f32_16x16x32_bf16 v[16:19], v[106:109], v[86:89], v[16:19]
	v_mfma_f32_16x16x32_bf16 v[12:15], v[94:97], v[90:93], v[12:15]
	v_mfma_f32_16x16x32_bf16 v[8:11], v[98:101], v[90:93], v[8:11]
	v_mfma_f32_16x16x32_bf16 v[4:7], v[102:105], v[90:93], v[4:7]
	v_mfma_f32_16x16x32_bf16 v[0:3], v[106:109], v[90:93], v[0:3]
	s_barrier
	s_cmpk_gt_u32 s14, 0x1f00
	s_cbranch_scc1 .Lf2_noissue
	s_add_u32 s9, s29, s21
	s_add_u32 m0, s9, 0x0
	s_nop 0
	global_load_lds_dwordx4 v150, s[30:31]
	s_add_u32 m0, s9, 0x1000
	s_add_u32 s22, s30, 0x40000
	s_addc_u32 s23, s31, 0
	global_load_lds_dwordx4 v150, s[22:23]
	s_add_u32 m0, s9, 0x2000
	s_add_u32 s22, s30, 0x80000
	s_addc_u32 s23, s31, 0
	global_load_lds_dwordx4 v150, s[22:23]
	s_add_u32 m0, s9, 0x4000
	s_nop 0
	global_load_lds_dwordx4 v150, s[34:35]
	s_add_u32 m0, s9, 0x5000
	s_add_u32 s22, s34, 0x40000
	s_addc_u32 s23, s35, 0
	global_load_lds_dwordx4 v150, s[22:23]
	s_add_u32 m0, s9, 0x6000
	s_add_u32 s22, s34, 0x80000
	s_addc_u32 s23, s35, 0
	global_load_lds_dwordx4 v150, s[22:23]
	s_add_u32 m0, s9, 0x7000
	s_add_u32 s22, s34, 0xc0000
	s_addc_u32 s23, s35, 0
	global_load_lds_dwordx4 v150, s[22:23]
	s_add_u32 s30, s30, 0x80
	s_addc_u32 s31, s31, 0
	s_add_u32 s34, s34, 0x80
	s_addc_u32 s35, s35, 0
.Lf2_noissue:
	s_xor_b32 s21, s21, 0x8000
	s_cmpk_eq_i32 s14, 0x1f80
	s_cbranch_scc0 .LBB0_560
	s_waitcnt vmcnt(0)
	s_andn2_b64 vcc, exec, s[2:3]
	s_barrier
	s_cbranch_vccnz .LBB0_542
	s_mul_i32 s0, s20, 0x60
	s_ashr_i32 s1, s0, 31
	s_lshl_b64 s[0:1], s[0:1], 13
	v_readlane_b32 s14, v249, 10
	v_readlane_b32 s15, v249, 11
	s_add_u32 s9, s14, s0
	s_addc_u32 s11, s15, s1
	s_and_b64 s[0:1], s[2:3], exec
	s_cselect_b32 s1, s11, 0
	s_cselect_b32 s0, s9, 0
	s_lshl_b32 s14, s19, 7
	s_ashr_i32 s15, s14, 31
	s_lshl_b64 s[14:15], s[14:15], 13
	s_add_u32 s9, s6, s14
	s_addc_u32 s11, s7, s15
	s_and_b64 s[14:15], s[2:3], exec
	s_cselect_b32 s15, s11, 0
	s_cselect_b32 s14, s9, 0
	v_lshl_add_u64 v[58:59], s[0:1], 0, v[56:57]
	v_lshl_add_u64 v[60:61], s[14:15], 0, v[56:57]
	v_lshl_add_u64 v[58:59], v[58:59], 0, v[152:153]
	v_lshl_add_u64 v[60:61], v[60:61], 0, v[152:153]
	s_mov_b64 s[0:1], 0x40000
	v_lshl_add_u64 v[82:83], v[58:59], 0, s[0:1]
	v_lshl_add_u64 v[86:87], v[60:61], 0, s[0:1]
	s_mov_b64 s[0:1], 0xc0000
	v_lshl_add_u64 v[90:91], v[60:61], 0, s[0:1]
	v_readfirstlane_b32 s0, v63
	s_mov_b32 m0, s0
	v_readfirstlane_b32 s0, v81
	s_mov_b64 s[14:15], 0x80000
	global_load_lds_dwordx4 v[58:59], off
	s_mov_b32 m0, s0
	v_readfirstlane_b32 s0, v80
	v_lshl_add_u64 v[84:85], v[58:59], 0, s[14:15]
	global_load_lds_dwordx4 v[82:83], off
	s_mov_b32 m0, s0
	v_readfirstlane_b32 s0, v79
	global_load_lds_dwordx4 v[84:85], off
	s_mov_b32 m0, s0
	v_readfirstlane_b32 s0, v78
	global_load_lds_dwordx4 v[60:61], off
	s_mov_b32 m0, s0
	v_readfirstlane_b32 s0, v77
	v_lshl_add_u64 v[88:89], v[60:61], 0, s[14:15]
	global_load_lds_dwordx4 v[86:87], off
	s_mov_b32 m0, s0
	v_readfirstlane_b32 s0, v76
	global_load_lds_dwordx4 v[88:89], off
	s_mov_b32 m0, s0
	s_nop 0
	global_load_lds_dwordx4 v[90:91], off
	s_branch .LBB0_542
